# v21 + the store drain and workgroup barrier at the end of the two P1 GEMM phases removed (the next prologue's in-order DMA waits and the seam's own drain+barrier cover them)
# baseline (speedup 1.0000x reference)
.LBB0_99:
.LBB0_100:
	s_xor_b64 s[0:1], s[54:55], -1
	s_mov_b64 s[54:55], 0
	s_andn2_b64 vcc, exec, s[0:1]
	s_mov_b64 s[0:1], s[66:67]
	s_cbranch_vccz .LBB0_214

.LBB0_197:
	s_mov_b64 s[96:97], s[4:5]
